# P0: w_in transpose loads de-serialised (32 W + 32 g loads in flight per item instead of one round trip per element)
# speedup vs baseline: 1.0247x; 1.0155x over previous
; #define LAS __attribute__((address_space(3)))
; __device__ __forceinline__ void p0_transpose_item(const float* W, int N, bf16_t* WT, int ldt, int col_off, const float* kscale, LAS float* scr, int item, int lane, int nscale_from = -1) {
;     const int nblk = N / 32, kb = item / nblk, nb = item % nblk, k0 = 64 * kb, n0 = 32 * nb;
; #pragma unroll 16
;     for (int i = 0; i < 32; ++i) { const int kk = 2 * i + (lane >> 5); const float s = (kscale ? kscale[k0 + kk] : 1.f) * ((nscale_from >= 0 && n0 >= nscale_from) ? -LOG2E : 1.f); scr[kk * 33 + (lane & 31)] = __builtin_nontemporal_load(W + (size_t)(k0 + kk) * N + n0 + (lane & 31)) * s; }
; __global__ void __launch_bounds__(NWAVES * 64, 2) fwd_megakernel(Args args) {
;     ...
;         for (int it = gw; it < I_IN; it += NGW) p0_transpose_item(w_in, NIN, Win_t, 1024, 0, g_in, scr, it, lane, C_GA);
.LBB0_5:
	s_or_b64 exec, exec, s[6:7]
	s_lshl_b32 s30, s93, 3
	s_add_u32 s2, s62, 0x200000
	s_addc_u32 s3, s63, 0
	s_load_dwordx16 s[76:91], s[0:1], 0x40
	v_writelane_b32 v254, s2, 4
	v_mov_b32_e32 v6, v0
	s_nop 0
	v_writelane_b32 v254, s3, 5
	v_readfirstlane_b32 s2, v6
	s_ashr_i32 s2, s2, 6
	s_lshl_b32 s3, s94, 3
	v_and_b32_e32 v68, 63, v6
	v_writelane_b32 v254, s3, 6
	s_add_i32 s3, s2, s3
	s_cmpk_gt_i32 s3, 0xa7f
	v_lshlrev_b32_e32 v66, 3, v68
	s_cbranch_scc1 .LBB0_42
	s_lshl_b32 s6, s2, 14
	v_lshrrev_b32_e32 v1, 3, v68
	v_and_b32_e32 v3, 56, v66
	s_add_i32 s7, s6, 0
	v_lshrrev_b32_e32 v2, 5, v68
	v_mul_u32_u24_e32 v7, 0x84, v3
	v_lshlrev_b32_e32 v8, 1, v3
	v_readlane_b32 s8, v254, 4
	v_lshlrev_b32_e32 v3, 2, v1
	s_waitcnt lgkmcnt(0)
	s_cmp_lg_u64 s[76:77], 0
	v_mov_b32_e32 v9, 0
	v_readlane_b32 s9, v254, 5
	v_add3_u32 v3, s7, v7, v3
	v_mul_u32_u24_e32 v7, 0x84, v2
	v_lshlrev_b32_e32 v6, 2, v6
	v_lshl_add_u64 v[4:5], s[8:9], 0, v[8:9]
	v_or_b32_e32 v7, s6, v7
	v_and_b32_e32 v8, 0x7c, v6
	s_cselect_b64 s[8:9], -1, 0
	v_or_b32_e32 v46, 8, v1
	v_or_b32_e32 v47, 16, v1
	v_or_b32_e32 v48, 24, v1
	v_add3_u32 v49, v7, v8, 0
	v_lshl_add_u64 v[6:7], s[78:79], 0, v[8:9]
	v_or_b32_e32 v50, 30, v2
	v_or_b32_e32 v51, 28, v2
	v_or_b32_e32 v52, 26, v2
	v_or_b32_e32 v53, 24, v2
	v_or_b32_e32 v54, 22, v2
	v_or_b32_e32 v55, 20, v2
	v_or_b32_e32 v56, 18, v2
	v_or_b32_e32 v57, 16, v2
	v_or_b32_e32 v58, 14, v2
	v_or_b32_e32 v59, 12, v2
	v_or_b32_e32 v60, 10, v2
	v_or_b32_e32 v61, 8, v2
	v_or_b32_e32 v62, 6, v2
	v_or_b32_e32 v63, 4, v2
	v_or_b32_e32 v64, 2, v2
	v_mov_b32_e32 v65, 0xbfb8aa3b
	s_movk_i32 s14, 0x5400
	s_movk_i32 s15, 0x7fff
	s_mov_b32 s20, 0xffff0000
	v_cndmask_b32_e64 v67, 0, 1, s[8:9]
	s_mov_b32 s21, s3
	v_and_b32_e32 v102, 31, v68
	v_mul_u32_u24_e32 v103, 0x5400, v2
	v_lshl_add_u32 v103, v102, 2, v103
	v_lshlrev_b32_e32 v102, 2, v2
	s_branch .LBB0_8

; __device__ __forceinline__ void p0_transpose_item(const float* W, int N, bf16_t* WT, int ldt, int col_off, const float* kscale, LAS float* scr, int item, int lane, int nscale_from = -1) {
;     const int nblk = N / 32, kb = item / nblk, nb = item % nblk, k0 = 64 * kb, n0 = 32 * nb;
; #pragma unroll 16
;     for (int i = 0; i < 32; ++i) { const int kk = 2 * i + (lane >> 5); const float s = (kscale ? kscale[k0 + kk] : 1.f) * ((nscale_from >= 0 && n0 >= nscale_from) ? -LOG2E : 1.f); scr[kk * 33 + (lane & 31)] = __builtin_nontemporal_load(W + (size_t)(k0 + kk) * N + n0 + (lane & 31)) * s; }
.LBB0_8:
	s_mul_hi_i32 s6, s21, 0x30c30c31
	s_lshr_b32 s7, s6, 31
	s_ashr_i32 s6, s6, 5
	s_add_i32 s6, s6, s7
	s_mul_i32 s7, s6, 0xa8
	s_sub_i32 s22, s21, s7
	s_lshl_b32 s10, s6, 6
	s_lshl_b32 s12, s22, 5
	s_cmpk_gt_i32 s22, 0x67
	s_cselect_b64 vcc, -1, 0
	s_ashr_i32 s13, s12, 31
	s_ashr_i32 s11, s10, 31
	v_cndmask_b32_e32 v69, 1.0, v65, vcc
	s_mul_i32 s16, s6, 0x150000
	s_lshl_b32 s17, s22, 7
	s_add_u32 s16, s16, s17
	s_add_u32 s16, s78, s16
	s_addc_u32 s17, s79, 0
	s_lshl_b32 s18, s6, 8
	s_add_u32 s18, s76, s18
	s_addc_u32 s19, s77, 0
	global_load_dword v70, v102, s[18:19]
	global_load_dword v71, v102, s[18:19] offset:8
	global_load_dword v72, v102, s[18:19] offset:16
	global_load_dword v73, v102, s[18:19] offset:24
	global_load_dword v74, v102, s[18:19] offset:32
	global_load_dword v75, v102, s[18:19] offset:40
	global_load_dword v76, v102, s[18:19] offset:48
	global_load_dword v77, v102, s[18:19] offset:56
	global_load_dword v78, v102, s[18:19] offset:64
	global_load_dword v79, v102, s[18:19] offset:72
	global_load_dword v80, v102, s[18:19] offset:80
	global_load_dword v81, v102, s[18:19] offset:88
	global_load_dword v82, v102, s[18:19] offset:96
	global_load_dword v83, v102, s[18:19] offset:104
	global_load_dword v84, v102, s[18:19] offset:112
	global_load_dword v85, v102, s[18:19] offset:120
	global_load_dword v86, v102, s[18:19] offset:128
	global_load_dword v87, v102, s[18:19] offset:136
	global_load_dword v88, v102, s[18:19] offset:144
	global_load_dword v89, v102, s[18:19] offset:152
	global_load_dword v90, v102, s[18:19] offset:160
	global_load_dword v91, v102, s[18:19] offset:168
	global_load_dword v92, v102, s[18:19] offset:176
	global_load_dword v93, v102, s[18:19] offset:184
	global_load_dword v94, v102, s[18:19] offset:192
	global_load_dword v95, v102, s[18:19] offset:200
	global_load_dword v96, v102, s[18:19] offset:208
	global_load_dword v97, v102, s[18:19] offset:216
	global_load_dword v98, v102, s[18:19] offset:224
	global_load_dword v99, v102, s[18:19] offset:232
	global_load_dword v100, v102, s[18:19] offset:240
	global_load_dword v101, v102, s[18:19] offset:248
	global_load_dword v8, v103, s[16:17] nt
	s_add_u32 s16, s16, 0xa800
	s_addc_u32 s17, s17, 0
	global_load_dword v9, v103, s[16:17] nt
	s_add_u32 s16, s16, 0xa800
	s_addc_u32 s17, s17, 0
	global_load_dword v10, v103, s[16:17] nt
	s_add_u32 s16, s16, 0xa800
	s_addc_u32 s17, s17, 0
	global_load_dword v11, v103, s[16:17] nt
	s_add_u32 s16, s16, 0xa800
	s_addc_u32 s17, s17, 0
	global_load_dword v12, v103, s[16:17] nt
	s_add_u32 s16, s16, 0xa800
	s_addc_u32 s17, s17, 0
	global_load_dword v13, v103, s[16:17] nt
	s_add_u32 s16, s16, 0xa800
	s_addc_u32 s17, s17, 0
	global_load_dword v14, v103, s[16:17] nt
	s_add_u32 s16, s16, 0xa800
	s_addc_u32 s17, s17, 0
	global_load_dword v15, v103, s[16:17] nt
	s_add_u32 s16, s16, 0xa800
	s_addc_u32 s17, s17, 0
	global_load_dword v16, v103, s[16:17] nt
	s_add_u32 s16, s16, 0xa800
	s_addc_u32 s17, s17, 0
	global_load_dword v17, v103, s[16:17] nt
	s_add_u32 s16, s16, 0xa800
	s_addc_u32 s17, s17, 0
	global_load_dword v18, v103, s[16:17] nt
	s_add_u32 s16, s16, 0xa800
	s_addc_u32 s17, s17, 0
	global_load_dword v19, v103, s[16:17] nt
	s_add_u32 s16, s16, 0xa800
	s_addc_u32 s17, s17, 0
	global_load_dword v20, v103, s[16:17] nt
	s_add_u32 s16, s16, 0xa800
	s_addc_u32 s17, s17, 0
	global_load_dword v21, v103, s[16:17] nt
	s_add_u32 s16, s16, 0xa800
	s_addc_u32 s17, s17, 0
	global_load_dword v22, v103, s[16:17] nt
	s_add_u32 s16, s16, 0xa800
	s_addc_u32 s17, s17, 0
	global_load_dword v23, v103, s[16:17] nt
	s_add_u32 s16, s16, 0xa800
	s_addc_u32 s17, s17, 0
	global_load_dword v24, v103, s[16:17] nt
	s_add_u32 s16, s16, 0xa800
	s_addc_u32 s17, s17, 0
	global_load_dword v25, v103, s[16:17] nt
	s_add_u32 s16, s16, 0xa800
	s_addc_u32 s17, s17, 0
	global_load_dword v26, v103, s[16:17] nt
	s_add_u32 s16, s16, 0xa800
	s_addc_u32 s17, s17, 0
	global_load_dword v27, v103, s[16:17] nt
	s_add_u32 s16, s16, 0xa800
	s_addc_u32 s17, s17, 0
	global_load_dword v28, v103, s[16:17] nt
	s_add_u32 s16, s16, 0xa800
	s_addc_u32 s17, s17, 0
	global_load_dword v29, v103, s[16:17] nt
	s_add_u32 s16, s16, 0xa800
	s_addc_u32 s17, s17, 0
	global_load_dword v30, v103, s[16:17] nt
	s_add_u32 s16, s16, 0xa800
	s_addc_u32 s17, s17, 0
	global_load_dword v31, v103, s[16:17] nt
	s_add_u32 s16, s16, 0xa800
	s_addc_u32 s17, s17, 0
	global_load_dword v32, v103, s[16:17] nt
	s_add_u32 s16, s16, 0xa800
	s_addc_u32 s17, s17, 0
	global_load_dword v33, v103, s[16:17] nt
	s_add_u32 s16, s16, 0xa800
	s_addc_u32 s17, s17, 0
	global_load_dword v34, v103, s[16:17] nt
	s_add_u32 s16, s16, 0xa800
	s_addc_u32 s17, s17, 0
	global_load_dword v35, v103, s[16:17] nt
	s_add_u32 s16, s16, 0xa800
	s_addc_u32 s17, s17, 0
	global_load_dword v36, v103, s[16:17] nt
	s_add_u32 s16, s16, 0xa800
	s_addc_u32 s17, s17, 0
	global_load_dword v37, v103, s[16:17] nt
	s_add_u32 s16, s16, 0xa800
	s_addc_u32 s17, s17, 0
	global_load_dword v38, v103, s[16:17] nt
	s_add_u32 s16, s16, 0xa800
	s_addc_u32 s17, s17, 0
	global_load_dword v39, v103, s[16:17] nt
	s_waitcnt vmcnt(31)
; __device__ __forceinline__ void p0_transpose_item(const float* W, int N, bf16_t* WT, int ldt, int col_off, const float* kscale, LAS float* scr, int item, int lane, int nscale_from = -1) {
;     ...
;     for (int i = 0; i < 32; ++i) { const int kk = 2 * i + (lane >> 5); const float s = (kscale ? kscale[k0 + kk] : 1.f) * ((nscale_from >= 0 && n0 >= nscale_from) ? -LOG2E : 1.f); scr[kk * 33 + (lane & 31)] = __builtin_nontemporal_load(W + (size_t)(k0 + kk) * N + n0 + (lane & 31)) * s; }
;     asm volatile("s_waitcnt lgkmcnt(0)" ::: "memory");
	v_mul_f32_e32 v6, v69, v70
	v_mul_f32_e32 v6, v8, v6
	ds_write_b32 v49, v6
	s_waitcnt vmcnt(30)
	v_mul_f32_e32 v6, v69, v71
	v_mul_f32_e32 v6, v9, v6
	ds_write_b32 v49, v6 offset:264
	s_waitcnt vmcnt(29)
	v_mul_f32_e32 v6, v69, v72
	v_mul_f32_e32 v6, v10, v6
	ds_write_b32 v49, v6 offset:528
	s_waitcnt vmcnt(28)
	v_mul_f32_e32 v6, v69, v73
	v_mul_f32_e32 v6, v11, v6
	ds_write_b32 v49, v6 offset:792
	s_waitcnt vmcnt(27)
	v_mul_f32_e32 v6, v69, v74
	v_mul_f32_e32 v6, v12, v6
	ds_write_b32 v49, v6 offset:1056
	s_waitcnt vmcnt(26)
	v_mul_f32_e32 v6, v69, v75
	v_mul_f32_e32 v6, v13, v6
	ds_write_b32 v49, v6 offset:1320
	s_waitcnt vmcnt(25)
	v_mul_f32_e32 v6, v69, v76
	v_mul_f32_e32 v6, v14, v6
	ds_write_b32 v49, v6 offset:1584
	s_waitcnt vmcnt(24)
	v_mul_f32_e32 v6, v69, v77
	v_mul_f32_e32 v6, v15, v6
	ds_write_b32 v49, v6 offset:1848
	s_waitcnt vmcnt(23)
	v_mul_f32_e32 v6, v69, v78
	v_mul_f32_e32 v6, v16, v6
	ds_write_b32 v49, v6 offset:2112
	s_waitcnt vmcnt(22)
	v_mul_f32_e32 v6, v69, v79
	v_mul_f32_e32 v6, v17, v6
	ds_write_b32 v49, v6 offset:2376
	s_waitcnt vmcnt(21)
	v_mul_f32_e32 v6, v69, v80
	v_mul_f32_e32 v6, v18, v6
	ds_write_b32 v49, v6 offset:2640
	s_waitcnt vmcnt(20)
	v_mul_f32_e32 v6, v69, v81
	v_mul_f32_e32 v6, v19, v6
	ds_write_b32 v49, v6 offset:2904
	s_waitcnt vmcnt(19)
	v_mul_f32_e32 v6, v69, v82
	v_mul_f32_e32 v6, v20, v6
	ds_write_b32 v49, v6 offset:3168
	s_waitcnt vmcnt(18)
	v_mul_f32_e32 v6, v69, v83
	v_mul_f32_e32 v6, v21, v6
	ds_write_b32 v49, v6 offset:3432
	s_waitcnt vmcnt(17)
	v_mul_f32_e32 v6, v69, v84
	v_mul_f32_e32 v6, v22, v6
	ds_write_b32 v49, v6 offset:3696
	s_waitcnt vmcnt(16)
	v_mul_f32_e32 v6, v69, v85
	v_mul_f32_e32 v6, v23, v6
	ds_write_b32 v49, v6 offset:3960
	s_waitcnt vmcnt(15)
	v_mul_f32_e32 v6, v69, v86
	v_mul_f32_e32 v6, v24, v6
	ds_write_b32 v49, v6 offset:4224
	s_waitcnt vmcnt(14)
	v_mul_f32_e32 v6, v69, v87
	v_mul_f32_e32 v6, v25, v6
	ds_write_b32 v49, v6 offset:4488
	s_waitcnt vmcnt(13)
	v_mul_f32_e32 v6, v69, v88
	v_mul_f32_e32 v6, v26, v6
	ds_write_b32 v49, v6 offset:4752
	s_waitcnt vmcnt(12)
	v_mul_f32_e32 v6, v69, v89
	v_mul_f32_e32 v6, v27, v6
	ds_write_b32 v49, v6 offset:5016
	s_waitcnt vmcnt(11)
	v_mul_f32_e32 v6, v69, v90
	v_mul_f32_e32 v6, v28, v6
	ds_write_b32 v49, v6 offset:5280
	s_waitcnt vmcnt(10)
	v_mul_f32_e32 v6, v69, v91
	v_mul_f32_e32 v6, v29, v6
	ds_write_b32 v49, v6 offset:5544
	s_waitcnt vmcnt(9)
	v_mul_f32_e32 v6, v69, v92
	v_mul_f32_e32 v6, v30, v6
	ds_write_b32 v49, v6 offset:5808
	s_waitcnt vmcnt(8)
	v_mul_f32_e32 v6, v69, v93
	v_mul_f32_e32 v6, v31, v6
	ds_write_b32 v49, v6 offset:6072
	s_waitcnt vmcnt(7)
	v_mul_f32_e32 v6, v69, v94
	v_mul_f32_e32 v6, v32, v6
	ds_write_b32 v49, v6 offset:6336
	s_waitcnt vmcnt(6)
	v_mul_f32_e32 v6, v69, v95
	v_mul_f32_e32 v6, v33, v6
	ds_write_b32 v49, v6 offset:6600
	s_waitcnt vmcnt(5)
	v_mul_f32_e32 v6, v69, v96
	v_mul_f32_e32 v6, v34, v6
	ds_write_b32 v49, v6 offset:6864
	s_waitcnt vmcnt(4)
	v_mul_f32_e32 v6, v69, v97
	v_mul_f32_e32 v6, v35, v6
	ds_write_b32 v49, v6 offset:7128
	s_waitcnt vmcnt(3)
	v_mul_f32_e32 v6, v69, v98
	v_mul_f32_e32 v6, v36, v6
	ds_write_b32 v49, v6 offset:7392
	s_waitcnt vmcnt(2)
	v_mul_f32_e32 v6, v69, v99
	v_mul_f32_e32 v6, v37, v6
	ds_write_b32 v49, v6 offset:7656
	s_waitcnt vmcnt(1)
	v_mul_f32_e32 v6, v69, v100
	v_mul_f32_e32 v6, v38, v6
	ds_write_b32 v49, v6 offset:7920
	s_waitcnt vmcnt(0)
	v_mul_f32_e32 v6, v69, v101
	v_mul_f32_e32 v6, v39, v6
	ds_write_b32 v49, v6 offset:8184
	s_branch .LBB0_7
